# W_pg weight-copy items (256) moved from the bx>=128 conversion tail to waves 0-1 of the bx<128 workgroups after their third W_in unit; third round of the tail shrinks to 64 items
# baseline (speedup 1.0000x reference)
; __device__ __forceinline__ void convert_weights(const Args& args, int first, int last, int worker, int nworkers, int lane) {
;     int it = first + worker;
;     if (it >= last) return;
; __global__ void __launch_bounds__(NWAVES * 64, 2) fwd_kernel(Args args) {
;     ...
;         if (G == 256 && bx >= 128) {
;             int tl_ = threadIdx.x; asm volatile("" : "+v"(tl_));
;             convert_weights(args, WI_P1 + WI_OUT, WI_ALL, (bx - 128) * NWAVES + wave, 128 * NWAVES, tl_ & 63);
;         }
.LBB0_405:
	s_xor_b64 s[2:3], s[88:89], -1
	s_and_b64 vcc, exec, s[2:3]
	s_cbranch_vccnz .LBB0_453
	v_readlane_b32 s1, v254, 22
	s_cmpk_lt_i32 s10, 0x80
	s_cbranch_scc1 .Lcv4_lo
	s_lshl_b32 s0, s10, 3
	s_add_i32 s25, s0, s1
	s_addk_i32 s25, 0xfc00
	s_branch .Lcv4_go
.Lcv4_lo:
	s_cmp_gt_u32 s1, 1
	s_cbranch_scc1 .LBB0_453
	s_lshl_b32 s0, s10, 1
	s_add_i32 s25, s0, s1
	s_addk_i32 s25, 0x840
.Lcv4_go:
	v_mov_b32_e32 v2, v0
	s_cmpk_gt_i32 s25, 0x93f
	s_cbranch_scc1 .LBB0_453
	s_add_i32 s33, s25, 0x3c0
	s_mov_b32 s26, 0
	s_cmpk_lt_i32 s25, 0xfec0
	s_movk_i32 s11, 0x400
	s_cbranch_scc1 .LBB0_413
	s_cmpk_gt_u32 s33, 0x2bf
	s_cbranch_scc0 .LBB0_414
	s_cmp_lt_u32 s25, 0xfffffc40
	s_cbranch_scc0 .LBB0_415
	s_cmpk_lt_u32 s33, 0x940
	s_cbranch_scc1 .LBB0_416
	s_cmpk_gt_u32 s33, 0xbff
	s_cbranch_scc0 .LBB0_417
	v_readlane_b32 s52, v254, 2
	v_readlane_b32 s62, v254, 12
	v_readlane_b32 s63, v254, 13
	v_readlane_b32 s64, v254, 14
	v_readlane_b32 s65, v254, 15
	s_add_i32 s24, s25, 0xfffff7c0
	s_mov_b64 s[0:1], 0
	v_readlane_b32 s53, v254, 3
	v_readlane_b32 s54, v254, 4
	v_readlane_b32 s55, v254, 5
	v_readlane_b32 s56, v254, 6
	v_readlane_b32 s57, v254, 7
	v_readlane_b32 s58, v254, 8
	v_readlane_b32 s59, v254, 9
	v_readlane_b32 s60, v254, 10
	v_readlane_b32 s61, v254, 11
	v_readlane_b32 s66, v254, 16
	v_readlane_b32 s67, v254, 17
	s_mov_b64 s[4:5], s[62:63]
	s_mov_b64 s[6:7], s[64:65]
	s_branch .LBB0_418

; __device__ __forceinline__ void convert_weights(const Args& args, int first, int last, int worker, int nworkers, int lane) {
;     ...
;     for (;;) {
;         const int nx = it + nworkers; const bool more = nx < last;
;         WItem nxt = cur; f32x4 vn[WR];
;         if (more) { nxt = witem_decode(args, nx, lane); witem_load(nxt, vn); }
;         witem_store(cur, v);
;         if (!more) break;
; #pragma unroll
;         for (int j = 0; j < WR; ++j) v[j] = vn[j];
;         cur = nxt; it = nx;
.LBB0_429:
	s_add_i32 s28, s33, 0x400
	s_cmpk_gt_i32 s33, 0x8ff
	s_cselect_b64 s[8:9], -1, 0
	s_cmpk_lt_i32 s33, 0x7c0
	s_cbranch_scc1 .Lcv3_keep
	s_cmpk_gt_i32 s33, 0xbbf
	s_cbranch_scc1 .Lcv3_keep
	s_add_i32 s98, s33, 0xfffff840
	s_lshr_b32 s99, s98, 1
	s_and_b32 s99, s99, 0xfffffffc
	s_and_b32 s28, s98, 3
	s_add_i32 s28, s28, s99
	s_addk_i32 s28, 0xbc0
	s_add_i32 s33, s28, 0xfffffc00
	s_and_b32 s99, s98, 4
	s_cselect_b32 s99, 1, 0
	s_cmpk_gt_u32 s98, 0x7f
	s_cselect_b32 s99, 1, s99
	s_cmp_lg_u32 s99, 0
	s_cselect_b64 s[8:9], -1, 0
